# merge phase counted wait: branch log-sum-exp loads issued before the GLA-half stores so the wait no longer includes store completion
# speedup vs baseline: 1.0020x; 1.0020x over previous
; __device__ __forceinline__ float bflo(unsigned u) { return __uint_as_float(u << 16); }
; __device__ __forceinline__ float bfhi(unsigned u) { return __uint_as_float(u & 0xffff0000u); }
; __device__ __forceinline__ float silu_f(float v) { return v / (1.0f + fexp2(-v * LOG2E)); }
; __device__ void merge_phase(const Params& p) {
;     ...
;         { const int hh = lane >> 4, sub = lane & 15;
;           const bf16_t* src = og + (size_t)tok * 1024 + hh * 256 + sub * 16;
;           const u32x4 a = *(const u32x4*)src, b = *(const u32x4*)(src + 8);
;           float xv[16];
; #pragma unroll
;           for (int j = 0; j < 4; ++j) { xv[2 * j] = bflo(a[j]); xv[2 * j + 1] = bfhi(a[j]); xv[8 + 2 * j] = bflo(b[j]); xv[8 + 2 * j + 1] = bfhi(b[j]); }
;           float s = 0.f;
; #pragma unroll
;           for (int j = 0; j < 16; ++j) s += xv[j];
;           s += __shfl_xor(s, 1); s += __shfl_xor(s, 2); s += __shfl_xor(s, 4); s += __shfl_xor(s, 8);
;           const float mean = s * (1.0f / 256.0f);
;           float q = 0.f;
; #pragma unroll
;           for (int j = 0; j < 16; ++j) { const float dlt = xv[j] - mean; q += dlt * dlt; }
;           q += __shfl_xor(q, 1); q += __shfl_xor(q, 2); q += __shfl_xor(q, 4); q += __shfl_xor(q, 8);
;           const float rstd = rsqrtf(q * (1.0f / 256.0f) + 1e-5f);
;           const bf16_t* rgp = h + (size_t)tok * HC + 2048 + hh * 256 + sub * 16;
;           const u32x4 ra = *(const u32x4*)rgp, rb = *(const u32x4*)(rgp + 8);
;           const float* ngp = p.norm_g + hh * 256 + sub * 16;
;           float ov[16];
; #pragma unroll
;           for (int j4 = 0; j4 < 4; ++j4) { const f32x4 ng = *(const f32x4*)(ngp + 4 * j4);
; #pragma unroll
;               for (int j = 0; j < 4; ++j) { const int e = 4 * j4 + j; const unsigned rw = (e < 8) ? ra[e >> 1] : rb[(e - 8) >> 1]; const float rv = (e & 1) ? bfhi(rw) : bflo(rw);
;                   ov[e] = (xv[e] - mean) * rstd * ng[j] * silu_f(rv); } }
.LBB0_100:
	v_ashrrev_i32_e32 v1, 31, v0
	v_lshlrev_b64 v[50:51], 11, v[0:1]
	v_lshl_add_u64 v[4:5], v[36:37], 0, v[50:51]
	global_load_dwordx4 v[24:27], v[4:5], off nt
	global_load_dwordx4 v[32:35], v[4:5], off offset:16 nt
	v_mov_b64_e32 v[4:5], s[92:93]
	v_mad_i64_i32 v[52:53], s[6:7], v0, s48, v[4:5]
	v_lshl_add_u64 v[4:5], v[52:53], 0, v[2:3]
	v_mov_b32_e32 v41, v3
	v_lshl_add_u64 v[4:5], v[4:5], 0, v[40:41]
	s_mov_b64 s[6:7], 0xd101000
	v_lshl_add_u64 v[6:7], v[4:5], 0, s[6:7]
	s_mov_b32 s6, 0xd101000
	v_add_co_u32_e32 v4, vcc, s6, v4
	s_waitcnt vmcnt(0)
	v_lshlrev_b32_e32 v58, 16, v27
	v_addc_co_u32_e32 v5, vcc, 0, v5, vcc
	global_load_dwordx4 v[28:31], v[4:5], off nt
	s_nop 0
	global_load_dwordx4 v[4:7], v[6:7], off offset:16 nt
	s_nop 0
	global_load_dwordx4 v[8:11], v[38:39], off offset:48
	global_load_dwordx4 v[12:15], v[38:39], off offset:32
	global_load_dwordx4 v[20:23], v[38:39], off
	global_load_dwordx4 v[16:19], v[38:39], off offset:16
	v_and_b32_e32 v59, 0xffff0000, v27
	v_lshlrev_b32_e32 v56, 16, v35
	v_and_b32_e32 v57, 0xffff0000, v35
	v_and_b32_e32 v61, 0xffff0000, v34
	v_and_b32_e32 v63, 0xffff0000, v26
	v_and_b32_e32 v65, 0xffff0000, v33
	v_lshlrev_b32_e32 v68, 16, v25
	v_and_b32_e32 v69, 0xffff0000, v25
	v_lshlrev_b32_e32 v70, 16, v32
	v_and_b32_e32 v71, 0xffff0000, v32
	s_waitcnt vmcnt(0)
	v_lshlrev_b32_e32 v27, 16, v31
	v_and_b32_e32 v31, 0xffff0000, v31
	v_mul_f32_e32 v35, 0xbfb8aa3b, v27
	v_exp_f32_e32 v54, v35
	v_mul_f32_e32 v35, 0xbfb8aa3b, v31
	v_exp_f32_e32 v55, v35
	s_nop 0
	v_pk_add_f32 v[54:55], v[54:55], 1.0 op_sel_hi:[1,0]
	s_nop 0
	v_div_scale_f32 v35, s[6:7], v55, v55, v31
	v_rcp_f32_e32 v43, v35
	s_nop 0
	v_fma_f32 v47, -v35, v43, 1.0
	v_fmac_f32_e32 v43, v47, v43
	v_div_scale_f32 v47, vcc, v31, v55, v31
	v_mul_f32_e32 v49, v47, v43
	v_fma_f32 v60, -v35, v49, v47
	v_fmac_f32_e32 v49, v60, v43
	v_fma_f32 v35, -v35, v49, v47
	v_div_fmas_f32 v35, v35, v43, v49
	v_div_fixup_f32 v55, v35, v55, v31
	v_div_scale_f32 v31, s[6:7], v54, v54, v27
	v_rcp_f32_e32 v35, v31
	v_lshlrev_b32_e32 v60, 16, v34
	v_fma_f32 v43, -v31, v35, 1.0
	v_fmac_f32_e32 v35, v43, v35
	v_div_scale_f32 v43, vcc, v27, v54, v27
	v_mul_f32_e32 v47, v43, v35
	v_fma_f32 v49, -v31, v47, v43
	v_fmac_f32_e32 v47, v49, v35
	v_fma_f32 v31, -v31, v47, v43
	v_div_fmas_f32 v31, v31, v35, v47
	v_div_fixup_f32 v54, v31, v54, v27
	v_lshlrev_b32_e32 v27, 16, v6
	v_and_b32_e32 v6, 0xffff0000, v6
	v_mul_f32_e32 v31, 0xbfb8aa3b, v27
	v_exp_f32_e32 v34, v31
	v_mul_f32_e32 v31, 0xbfb8aa3b, v6
	v_exp_f32_e32 v35, v31
	s_nop 0
	v_pk_add_f32 v[34:35], v[34:35], 1.0 op_sel_hi:[1,0]
	s_nop 0
	v_div_scale_f32 v31, s[6:7], v35, v35, v6
	v_rcp_f32_e32 v43, v31
	s_nop 0
	v_fma_f32 v47, -v31, v43, 1.0
	v_fmac_f32_e32 v43, v47, v43
	v_div_scale_f32 v47, vcc, v6, v35, v6
	v_mul_f32_e32 v49, v47, v43
	v_fma_f32 v62, -v31, v49, v47
	v_fmac_f32_e32 v49, v62, v43
	v_fma_f32 v31, -v31, v49, v47
	v_div_fmas_f32 v31, v31, v43, v49
	v_div_fixup_f32 v35, v31, v35, v6
	v_div_scale_f32 v6, s[6:7], v34, v34, v27
	v_rcp_f32_e32 v31, v6
	v_lshlrev_b32_e32 v62, 16, v26
	v_fma_f32 v43, -v6, v31, 1.0
	v_fmac_f32_e32 v31, v43, v31
	v_div_scale_f32 v43, vcc, v27, v34, v27
	v_mul_f32_e32 v47, v43, v31
	v_fma_f32 v49, -v6, v47, v43
	v_fmac_f32_e32 v47, v49, v31
	v_fma_f32 v6, -v6, v47, v43
	v_div_fmas_f32 v6, v6, v31, v47
	v_div_fixup_f32 v34, v6, v34, v27
	v_lshlrev_b32_e32 v6, 16, v30
	v_and_b32_e32 v30, 0xffff0000, v30
	v_mul_f32_e32 v26, 0xbfb8aa3b, v6
	v_mul_f32_e32 v27, 0xbfb8aa3b, v30
	v_exp_f32_e32 v26, v26
	v_exp_f32_e32 v27, v27
	s_nop 0
	v_pk_add_f32 v[26:27], v[26:27], 1.0 op_sel_hi:[1,0]
	s_nop 0
	v_div_scale_f32 v31, s[6:7], v27, v27, v30
	v_rcp_f32_e32 v43, v31
	s_nop 0
	v_fma_f32 v47, -v31, v43, 1.0
	v_fmac_f32_e32 v43, v47, v43
	v_div_scale_f32 v47, vcc, v30, v27, v30
	v_mul_f32_e32 v49, v47, v43
	v_fma_f32 v64, -v31, v49, v47
	v_fmac_f32_e32 v49, v64, v43
	v_fma_f32 v31, -v31, v49, v47
	v_div_fmas_f32 v31, v31, v43, v49
	v_div_fixup_f32 v27, v31, v27, v30
	v_div_scale_f32 v30, s[6:7], v26, v26, v6
	v_rcp_f32_e32 v31, v30
	v_lshlrev_b32_e32 v64, 16, v33
	v_fma_f32 v43, -v30, v31, 1.0
	v_fmac_f32_e32 v31, v43, v31
	v_div_scale_f32 v43, vcc, v6, v26, v6
	v_mul_f32_e32 v47, v43, v31
	v_fma_f32 v49, -v30, v47, v43
	v_fmac_f32_e32 v47, v49, v31
	v_fma_f32 v30, -v30, v47, v43
	v_div_fmas_f32 v30, v30, v31, v47
	v_div_fixup_f32 v26, v30, v26, v6
	v_lshlrev_b32_e32 v6, 16, v5
	v_and_b32_e32 v5, 0xffff0000, v5
	v_mul_f32_e32 v30, 0xbfb8aa3b, v6
	v_mul_f32_e32 v31, 0xbfb8aa3b, v5
	v_exp_f32_e32 v30, v30
	v_exp_f32_e32 v31, v31
	s_nop 0
	v_pk_add_f32 v[30:31], v[30:31], 1.0 op_sel_hi:[1,0]
	s_nop 0
	v_div_scale_f32 v33, s[6:7], v31, v31, v5
	v_rcp_f32_e32 v43, v33
	s_nop 0
	v_fma_f32 v47, -v33, v43, 1.0
	v_fmac_f32_e32 v43, v47, v43
	v_div_scale_f32 v47, vcc, v5, v31, v5
	v_mul_f32_e32 v49, v47, v43
	v_fma_f32 v66, -v33, v49, v47
	v_fmac_f32_e32 v49, v66, v43
	v_fma_f32 v33, -v33, v49, v47
	v_div_fmas_f32 v33, v33, v43, v49
	v_div_fixup_f32 v31, v33, v31, v5
	v_div_scale_f32 v5, s[6:7], v30, v30, v6
	v_rcp_f32_e32 v33, v5
	s_nop 0
	v_fma_f32 v43, -v5, v33, 1.0
	v_fmac_f32_e32 v33, v43, v33
	v_div_scale_f32 v43, vcc, v6, v30, v6
	v_mul_f32_e32 v47, v43, v33
	v_fma_f32 v49, -v5, v47, v43
	v_fmac_f32_e32 v47, v49, v33
	v_fma_f32 v5, -v5, v47, v43
	v_div_fmas_f32 v5, v5, v33, v47
	v_div_fixup_f32 v30, v5, v30, v6
	v_lshlrev_b32_e32 v5, 16, v29
	v_and_b32_e32 v6, 0xffff0000, v29
	v_mul_f32_e32 v25, 0xbfb8aa3b, v5
	v_exp_f32_e32 v66, v25
	v_mul_f32_e32 v25, 0xbfb8aa3b, v6
	v_exp_f32_e32 v67, v25
	s_nop 0
	v_pk_add_f32 v[66:67], v[66:67], 1.0 op_sel_hi:[1,0]
	s_nop 0
; __device__ __forceinline__ float bflo(unsigned u) { return __uint_as_float(u << 16); }
; __device__ __forceinline__ float bfhi(unsigned u) { return __uint_as_float(u & 0xffff0000u); }
; __device__ __forceinline__ float silu_f(float v) { return v / (1.0f + fexp2(-v * LOG2E)); }
; __device__ void merge_phase(const Params& p) {
;     ...
;           float s = 0.f;
; #pragma unroll
;           for (int j = 0; j < 16; ++j) s += xv[j];
;           s += __shfl_xor(s, 1); s += __shfl_xor(s, 2); s += __shfl_xor(s, 4); s += __shfl_xor(s, 8);
;           const float mean = s * (1.0f / 256.0f);
;           float q = 0.f;
; #pragma unroll
;           for (int j = 0; j < 16; ++j) { const float dlt = xv[j] - mean; q += dlt * dlt; }
;           q += __shfl_xor(q, 1); q += __shfl_xor(q, 2); q += __shfl_xor(q, 4); q += __shfl_xor(q, 8);
;           const float rstd = rsqrtf(q * (1.0f / 256.0f) + 1e-5f);
;           const bf16_t* rgp = h + (size_t)tok * HC + 2048 + hh * 256 + sub * 16;
;           const u32x4 ra = *(const u32x4*)rgp, rb = *(const u32x4*)(rgp + 8);
;           const float* ngp = p.norm_g + hh * 256 + sub * 16;
;           float ov[16];
; #pragma unroll
;           for (int j4 = 0; j4 < 4; ++j4) { const f32x4 ng = *(const f32x4*)(ngp + 4 * j4);
; #pragma unroll
;               for (int j = 0; j < 4; ++j) { const int e = 4 * j4 + j; const unsigned rw = (e < 8) ? ra[e >> 1] : rb[(e - 8) >> 1]; const float rv = (e & 1) ? bfhi(rw) : bflo(rw);
;                   ov[e] = (xv[e] - mean) * rstd * ng[j] * silu_f(rv); } }
	v_div_scale_f32 v25, s[6:7], v67, v67, v6
	v_rcp_f32_e32 v29, v25
	s_nop 0
	v_fma_f32 v33, -v25, v29, 1.0
	v_fmac_f32_e32 v29, v33, v29
	v_div_scale_f32 v33, vcc, v6, v67, v6
	v_mul_f32_e32 v43, v33, v29
	v_fma_f32 v47, -v25, v43, v33
	v_fmac_f32_e32 v43, v47, v29
	v_fma_f32 v25, -v25, v43, v33
	v_div_fmas_f32 v25, v25, v29, v43
	v_div_fixup_f32 v67, v25, v67, v6
	v_div_scale_f32 v6, s[6:7], v66, v66, v5
	v_rcp_f32_e32 v25, v6
	s_nop 0
	v_fma_f32 v29, -v6, v25, 1.0
	v_fmac_f32_e32 v25, v29, v25
	v_div_scale_f32 v29, vcc, v5, v66, v5
	v_mul_f32_e32 v33, v29, v25
	v_fma_f32 v43, -v6, v33, v29
	v_fmac_f32_e32 v33, v43, v25
	v_fma_f32 v6, -v6, v33, v29
	v_div_fmas_f32 v6, v6, v25, v33
	v_div_fixup_f32 v66, v6, v66, v5
	v_lshlrev_b32_e32 v6, 16, v4
	v_and_b32_e32 v25, 0xffff0000, v4
	v_mul_f32_e32 v4, 0xbfb8aa3b, v6
	v_mul_f32_e32 v5, 0xbfb8aa3b, v25
	v_exp_f32_e32 v4, v4
	v_exp_f32_e32 v5, v5
	s_nop 0
	v_pk_add_f32 v[4:5], v[4:5], 1.0 op_sel_hi:[1,0]
	s_nop 0
	v_div_scale_f32 v29, s[6:7], v5, v5, v25
	v_rcp_f32_e32 v32, v29
	s_nop 0
	v_fma_f32 v33, -v29, v32, 1.0
	v_fmac_f32_e32 v32, v33, v32
	v_div_scale_f32 v33, vcc, v25, v5, v25
	v_mul_f32_e32 v43, v33, v32
	v_fma_f32 v47, -v29, v43, v33
	v_fmac_f32_e32 v43, v47, v32
	v_fma_f32 v29, -v29, v43, v33
	v_div_fmas_f32 v29, v29, v32, v43
	v_div_fixup_f32 v5, v29, v5, v25
	v_div_scale_f32 v25, s[6:7], v4, v4, v6
	v_rcp_f32_e32 v29, v25
	s_nop 0
	v_fma_f32 v32, -v25, v29, 1.0
	v_fmac_f32_e32 v29, v32, v29
	v_div_scale_f32 v32, vcc, v6, v4, v6
	v_mul_f32_e32 v33, v32, v29
	v_fma_f32 v43, -v25, v33, v32
	v_fmac_f32_e32 v33, v43, v29
	v_fma_f32 v25, -v25, v33, v32
	v_div_fmas_f32 v25, v25, v29, v33
	v_lshlrev_b32_e32 v29, 16, v28
	v_and_b32_e32 v28, 0xffff0000, v28
	v_div_fixup_f32 v4, v25, v4, v6
	v_lshlrev_b32_e32 v32, 16, v24
	v_and_b32_e32 v33, 0xffff0000, v24
	v_mul_f32_e32 v24, 0xbfb8aa3b, v29
	v_mul_f32_e32 v25, 0xbfb8aa3b, v28
	v_exp_f32_e32 v24, v24
	v_exp_f32_e32 v25, v25
	v_add_f32_e32 v6, 0, v32
	v_add_f32_e32 v6, v6, v33
	v_add_f32_e32 v6, v6, v68
	v_pk_add_f32 v[24:25], v[24:25], 1.0 op_sel_hi:[1,0]
	v_add_f32_e32 v6, v6, v69
	v_div_scale_f32 v43, s[6:7], v25, v25, v28
	v_rcp_f32_e32 v47, v43
	v_add_f32_e32 v6, v6, v62
	v_add_f32_e32 v6, v6, v63
	v_add_f32_e32 v6, v6, v58
	v_fma_f32 v49, -v43, v47, 1.0
	v_fmac_f32_e32 v47, v49, v47
	v_div_scale_f32 v49, vcc, v28, v25, v28
	v_mul_f32_e32 v76, v49, v47
	v_fma_f32 v77, -v43, v76, v49
	v_fmac_f32_e32 v76, v77, v47
	v_fma_f32 v43, -v43, v76, v49
	v_div_fmas_f32 v43, v43, v47, v76
	v_div_fixup_f32 v25, v43, v25, v28
	v_div_scale_f32 v28, s[6:7], v24, v24, v29
	v_rcp_f32_e32 v43, v28
	v_add_f32_e32 v6, v6, v59
	v_add_f32_e32 v6, v6, v70
	v_add_f32_e32 v6, v6, v71
	v_fma_f32 v47, -v28, v43, 1.0
	v_fmac_f32_e32 v43, v47, v43
	v_div_scale_f32 v47, vcc, v29, v24, v29
	v_add_f32_e32 v6, v6, v64
	v_mul_f32_e32 v49, v47, v43
	v_add_f32_e32 v6, v6, v65
	v_fma_f32 v76, -v28, v49, v47
	v_add_f32_e32 v6, v6, v60
	v_fmac_f32_e32 v49, v76, v43
	v_add_f32_e32 v6, v6, v61
	v_fma_f32 v28, -v28, v49, v47
	v_add_f32_e32 v6, v6, v56
	v_div_fmas_f32 v28, v28, v43, v49
	v_add_f32_e32 v6, v6, v57
	v_div_fixup_f32 v24, v28, v24, v29
	v_mov_b32_e32 v43, v3
	v_mov_b32_e32 v47, v3
	v_mov_b32_e32 v49, v3
	s_nop 1
	v_add_f32_dpp v6, v6, v6 quad_perm:[1,0,3,2] row_mask:0xf bank_mask:0xf
	s_nop 1
	v_add_f32_dpp v6, v6, v6 quad_perm:[2,3,0,1] row_mask:0xf bank_mask:0xf
	s_nop 1
	v_add_f32_dpp v6, v6, v6 row_half_mirror row_mask:0xf bank_mask:0xf
	s_nop 1
	v_add_f32_dpp v6, v6, v6 row_mirror row_mask:0xf bank_mask:0xf
	v_mul_f32_e32 v6, 0x3b800000, v6
	v_pk_add_f32 v[28:29], v[32:33], v[6:7] op_sel_hi:[1,0] neg_lo:[0,1] neg_hi:[0,1]
	v_pk_add_f32 v[68:69], v[68:69], v[6:7] op_sel_hi:[1,0] neg_lo:[0,1] neg_hi:[0,1]
	v_pk_mul_f32 v[32:33], v[28:29], v[28:29]
	v_pk_mul_f32 v[76:77], v[68:69], v[68:69]
	v_pk_add_f32 v[62:63], v[62:63], v[6:7] op_sel_hi:[1,0] neg_lo:[0,1] neg_hi:[0,1]
	v_pk_add_f32 v[58:59], v[58:59], v[6:7] op_sel_hi:[1,0] neg_lo:[0,1] neg_hi:[0,1]
	v_pk_add_f32 v[70:71], v[70:71], v[6:7] op_sel_hi:[1,0] neg_lo:[0,1] neg_hi:[0,1]
	v_pk_add_f32 v[64:65], v[64:65], v[6:7] op_sel_hi:[1,0] neg_lo:[0,1] neg_hi:[0,1]
	v_pk_add_f32 v[60:61], v[60:61], v[6:7] op_sel_hi:[1,0] neg_lo:[0,1] neg_hi:[0,1]
	v_pk_add_f32 v[56:57], v[56:57], v[6:7] op_sel_hi:[1,0] neg_lo:[0,1] neg_hi:[0,1]
	v_add_f32_e32 v6, v32, v33
	v_add_f32_e32 v6, v76, v6
	v_pk_mul_f32 v[78:79], v[62:63], v[62:63]
	v_add_f32_e32 v6, v77, v6
	v_add_f32_e32 v6, v78, v6
	v_pk_mul_f32 v[80:81], v[58:59], v[58:59]
	v_add_f32_e32 v6, v79, v6
	v_add_f32_e32 v6, v80, v6
	v_pk_mul_f32 v[82:83], v[70:71], v[70:71]
	v_add_f32_e32 v6, v81, v6
	v_add_f32_e32 v6, v82, v6
	v_pk_mul_f32 v[84:85], v[64:65], v[64:65]
	v_add_f32_e32 v6, v83, v6
	v_add_f32_e32 v6, v84, v6
	v_pk_mul_f32 v[86:87], v[60:61], v[60:61]
	v_add_f32_e32 v6, v85, v6
	v_add_f32_e32 v6, v86, v6
	v_pk_mul_f32 v[88:89], v[56:57], v[56:57]
	v_add_f32_e32 v6, v87, v6
	v_add_f32_e32 v6, v88, v6
	v_add_f32_e32 v6, v89, v6
	s_nop 1
	v_add_f32_dpp v6, v6, v6 quad_perm:[1,0,3,2] row_mask:0xf bank_mask:0xf
	s_nop 1
	v_add_f32_dpp v6, v6, v6 quad_perm:[2,3,0,1] row_mask:0xf bank_mask:0xf
	s_nop 1
	v_add_f32_dpp v6, v6, v6 row_half_mirror row_mask:0xf bank_mask:0xf
	s_nop 1
	v_add_f32_dpp v6, v6, v6 row_mirror row_mask:0xf bank_mask:0xf
	v_fmamk_f32 v6, v6, 0x3b800000, v213
	v_cmp_gt_f32_e32 vcc, s15, v6
	v_mul_f32_e32 v32, 0x4b800000, v6
	s_nop 0
	v_cndmask_b32_e32 v6, v6, v32, vcc
	v_rsq_f32_e32 v6, v6
	s_nop 0
	v_mul_f32_e32 v32, 0x45800000, v6
	v_cndmask_b32_e32 v6, v6, v32, vcc
	v_pk_mul_f32 v[28:29], v[28:29], v[6:7] op_sel_hi:[1,0]
	s_nop 0
; __device__ __forceinline__ unsigned cvt_pk_bf16(float lo, float hi) { const f32x2v v = {lo, hi}; const b16x2v r = __builtin_convertvector(v, b16x2v); return __builtin_bit_cast(unsigned, r); }
; __device__ __forceinline__ float bflo(unsigned u) { return __uint_as_float(u << 16); }
; __device__ __forceinline__ float bfhi(unsigned u) { return __uint_as_float(u & 0xffff0000u); }
; __device__ __forceinline__ float fexp2(float x) { return __builtin_amdgcn_exp2f(x); }
; __device__ void merge_phase(const Params& p) {
;     ...
;           u32x4 o0, o1;
; #pragma unroll
;           for (int j = 0; j < 4; ++j) { o0[j] = cvt_pk_bf16(ov[2 * j], ov[2 * j + 1]); o1[j] = cvt_pk_bf16(ov[8 + 2 * j], ov[8 + 2 * j + 1]); }
;           bf16_t* dst = mix + (size_t)tok * DM + hh * 256 + sub * 16;
;           *(u32x4*)dst = o0; *(u32x4*)(dst + 8) = o1; }
;         { const int hd = lane >> 3, sub = lane & 7;
;           const float l0 = lse[(size_t)tok * 8 + hd], l1 = lse[(size_t)T_TOK * 8 + (size_t)tok * 8 + hd], l2 = lse[(size_t)2 * T_TOK * 8 + (size_t)tok * 8 + hd];
;           const float m = fmaxf(l0, fmaxf(l1, l2));
;           float e0 = fexp2((l0 - m) * LOG2E), e1 = fexp2((l1 - m) * LOG2E), e2 = fexp2((l2 - m) * LOG2E);
;           const float inv = 1.0f / (e0 + e1 + e2); e0 *= inv; e1 *= inv; e2 *= inv;
;           const size_t so = (size_t)tok * 1024 + hd * 128 + sub * 16;
;           u32x4 o[2];
; #pragma unroll
;           for (int hf = 0; hf < 2; ++hf) { const u32x4 a = *(const u32x4*)(od0 + so + 8 * hf), b = *(const u32x4*)(od1 + so + 8 * hf), c = *(const u32x4*)(od2 + so + 8 * hf);
; #pragma unroll
;               for (int j = 0; j < 4; ++j) o[hf][j] = cvt_pk_bf16(e0 * bflo(a[j]) + e1 * bflo(b[j]) + e2 * bflo(c[j]), e0 * bfhi(a[j]) + e1 * bfhi(b[j]) + e2 * bfhi(c[j])); }
	v_pk_mul_f32 v[20:21], v[20:21], v[28:29]
	s_nop 0
	v_pk_mul_f32 v[20:21], v[24:25], v[20:21]
	v_pk_mul_f32 v[24:25], v[68:69], v[6:7] op_sel_hi:[1,0]
	s_nop 0
	v_pk_mul_f32 v[22:23], v[22:23], v[24:25]
	v_pk_mul_f32 v[24:25], v[62:63], v[6:7] op_sel_hi:[1,0]
	v_pk_mul_f32 v[22:23], v[66:67], v[22:23]
	v_pk_mul_f32 v[16:17], v[16:17], v[24:25]
	v_pk_mul_f32 v[24:25], v[58:59], v[6:7] op_sel_hi:[1,0]
	v_pk_mul_f32 v[16:17], v[26:27], v[16:17]
	v_pk_mul_f32 v[18:19], v[18:19], v[24:25]
	v_pk_mul_f32 v[24:25], v[70:71], v[6:7] op_sel_hi:[1,0]
	v_pk_mul_f32 v[18:19], v[54:55], v[18:19]
	v_pk_mul_f32 v[12:13], v[12:13], v[24:25]
	s_nop 0
	v_pk_mul_f32 v[12:13], v[4:5], v[12:13]
	v_pk_mul_f32 v[4:5], v[64:65], v[6:7] op_sel_hi:[1,0]
	s_nop 0
	v_pk_mul_f32 v[4:5], v[14:15], v[4:5]
	s_nop 0
	v_pk_mul_f32 v[14:15], v[30:31], v[4:5]
	v_pk_mul_f32 v[4:5], v[60:61], v[6:7] op_sel_hi:[1,0]
	s_nop 0
	v_pk_mul_f32 v[4:5], v[8:9], v[4:5]
	v_lshlrev_b32_e32 v8, 16, v7
	v_and_b32_e32 v9, 0xffff0000, v7
	v_pk_mul_f32 v[24:25], v[34:35], v[4:5]
	v_mul_f32_e32 v4, 0xbfb8aa3b, v8
	v_mul_f32_e32 v5, 0xbfb8aa3b, v9
	v_exp_f32_e32 v4, v4
	v_exp_f32_e32 v5, v5
	v_pk_mul_f32 v[6:7], v[56:57], v[6:7] op_sel_hi:[1,0]
	v_pk_add_f32 v[4:5], v[4:5], 1.0 op_sel_hi:[1,0]
	v_pk_mul_f32 v[6:7], v[10:11], v[6:7]
	v_div_scale_f32 v10, s[6:7], v5, v5, v9
	v_rcp_f32_e32 v11, v10
	s_nop 0
	v_fma_f32 v26, -v10, v11, 1.0
	v_fmac_f32_e32 v11, v26, v11
	v_div_scale_f32 v26, vcc, v9, v5, v9
	v_mul_f32_e32 v27, v26, v11
	v_fma_f32 v28, -v10, v27, v26
	v_fmac_f32_e32 v27, v28, v11
	v_fma_f32 v10, -v10, v27, v26
	v_div_fmas_f32 v10, v10, v11, v27
	v_div_fixup_f32 v5, v10, v5, v9
	v_div_scale_f32 v9, s[6:7], v4, v4, v8
	v_rcp_f32_e32 v10, v9
	s_mov_b32 s6, 0x100000
	v_fma_f32 v11, -v9, v10, 1.0
	v_fmac_f32_e32 v10, v11, v10
	v_div_scale_f32 v11, vcc, v8, v4, v8
	v_mul_f32_e32 v26, v11, v10
	v_fma_f32 v27, -v9, v26, v11
	v_fmac_f32_e32 v26, v27, v10
	v_fma_f32 v9, -v9, v26, v11
	v_div_fmas_f32 v9, v9, v10, v26
	v_div_fixup_f32 v4, v9, v4, v8
	v_cvt_pk_bf16_f32 v8, v12, v13
	v_lshlrev_b64 v[12:13], 13, v[0:1]
	v_sub_co_u32_e32 v12, vcc, 0, v12
	v_pk_mul_f32 v[26:27], v[4:5], v[6:7]
	s_nop 0
	v_subb_co_u32_e32 v13, vcc, 0, v13, vcc
	v_cvt_pk_bf16_f32 v6, v16, v17
	v_lshl_add_u64 v[16:17], v[52:53], 0, v[12:13]
	v_lshl_add_u64 v[12:13], v[16:17], 0, v[2:3]
	v_cvt_pk_bf16_f32 v4, v20, v21
	v_cvt_pk_bf16_f32 v5, v22, v23
	v_cvt_pk_bf16_f32 v7, v18, v19
	v_lshl_add_u64 v[12:13], v[12:13], 0, v[40:41]
	v_cvt_pk_bf16_f32 v9, v14, v15
	v_cvt_pk_bf16_f32 v10, v24, v25
	v_cvt_pk_bf16_f32 v11, v26, v27
	v_lshlrev_b64 v[128:129], 5, v[0:1]
	v_lshl_add_u64 v[128:129], s[12:13], 0, v[128:129]
	v_lshl_add_u64 v[128:129], v[128:129], 0, v[42:43]
	v_add_co_u32_e32 v130, vcc, s9, v128
	s_nop 1
	v_addc_co_u32_e32 v131, vcc, 0, v129, vcc
	global_load_dword v100, v[128:129], off nt
	global_load_dword v101, v[130:131], off nt
	v_add_co_u32_e32 v132, vcc, s6, v128
	s_nop 1
	v_addc_co_u32_e32 v133, vcc, 0, v129, vcc
	global_load_dword v102, v[132:133], off nt
	global_store_dwordx4 v[12:13], v[4:7], off
	global_store_dwordx4 v[12:13], v[8:11], off offset:16
	s_nop 0
	v_add_u32_e32 v0, s8, v0
	s_waitcnt vmcnt(2)
	v_mov_b32_e32 v1, v100
	v_mov_b32_e32 v6, v101
	v_mov_b32_e32 v4, v102
	v_max3_f32 v5, v1, v6, v4
	v_sub_f32_e32 v1, v1, v5
	v_mul_f32_e32 v1, 0x3fb8aa3b, v1
	v_exp_f32_e32 v21, v1
	v_sub_f32_e32 v1, v6, v5
	v_mul_f32_e32 v1, 0x3fb8aa3b, v1
	v_exp_f32_e32 v20, v1
	v_sub_f32_e32 v1, v4, v5
	v_mul_f32_e32 v1, 0x3fb8aa3b, v1
	v_exp_f32_e32 v1, v1
	v_add_f32_e32 v4, v21, v20
	v_add_f32_e32 v4, v1, v4
	v_div_scale_f32 v5, s[6:7], v4, v4, 1.0
	v_rcp_f32_e32 v6, v5
	s_nop 0
	v_fma_f32 v7, -v5, v6, 1.0
	v_fmac_f32_e32 v6, v7, v6
	v_div_scale_f32 v7, vcc, 1.0, v4, 1.0
	v_mul_f32_e32 v8, v7, v6
	v_fma_f32 v9, -v5, v8, v7
	v_fmac_f32_e32 v8, v9, v6
	v_fma_f32 v5, -v5, v8, v7
	v_div_fmas_f32 v5, v5, v6, v8
	v_div_fixup_f32 v22, v5, v4, 1.0
	v_or_b32_e32 v5, v51, v45
	v_or_b32_e32 v4, v50, v44
	v_lshl_add_u64 v[8:9], s[54:55], 0, v[4:5]
	v_lshl_add_u64 v[12:13], s[10:11], 0, v[4:5]
	v_lshl_add_u64 v[32:33], s[24:25], 0, v[4:5]
	global_load_dwordx4 v[4:7], v[8:9], off offset:16 nt
	global_load_dwordx4 v[24:27], v[8:9], off nt
	s_nop 0
	global_load_dwordx4 v[8:11], v[12:13], off offset:16 nt
	global_load_dwordx4 v[28:31], v[12:13], off nt
	s_nop 0
	global_load_dwordx4 v[12:15], v[32:33], off offset:16 nt
	s_nop 0
	global_load_dwordx4 v[32:35], v[32:33], off nt
	v_mul_f32_e32 v18, v1, v22
	v_pk_mul_f32 v[50:51], v[20:21], v[22:23] op_sel_hi:[1,0]
	v_cmp_lt_i32_e32 vcc, s18, v0
	s_or_b64 s[2:3], vcc, s[2:3]
	s_waitcnt vmcnt(4)
; __device__ __forceinline__ unsigned cvt_pk_bf16(float lo, float hi) { const f32x2v v = {lo, hi}; const b16x2v r = __builtin_convertvector(v, b16x2v); return __builtin_bit_cast(unsigned, r); }
; __device__ __forceinline__ float bflo(unsigned u) { return __uint_as_float(u << 16); }
; __device__ __forceinline__ float bfhi(unsigned u) { return __uint_as_float(u & 0xffff0000u); }
; __device__ void merge_phase(const Params& p) {
;     ...
;           for (int hf = 0; hf < 2; ++hf) { const u32x4 a = *(const u32x4*)(od0 + so + 8 * hf), b = *(const u32x4*)(od1 + so + 8 * hf), c = *(const u32x4*)(od2 + so + 8 * hf);
; #pragma unroll
;               for (int j = 0; j < 4; ++j) o[hf][j] = cvt_pk_bf16(e0 * bflo(a[j]) + e1 * bflo(b[j]) + e2 * bflo(c[j]), e0 * bfhi(a[j]) + e1 * bfhi(b[j]) + e2 * bfhi(c[j])); }
;           bf16_t* dst = mix + (size_t)tok * DM + 1024 + hd * 128 + sub * 16;
;           *(u32x4*)dst = o[0]; *(u32x4*)(dst + 8) = o[1]; }
	v_lshlrev_b32_e32 v22, 16, v24
	v_and_b32_e32 v21, 0xffff0000, v24
	s_waitcnt vmcnt(2)
	v_and_b32_e32 v23, 0xffff0000, v28
	v_lshlrev_b32_e32 v20, 16, v28
	v_pk_mul_f32 v[22:23], v[50:51], v[22:23] op_sel:[1,0] op_sel_hi:[0,1]
	v_pk_fma_f32 v[20:21], v[50:51], v[20:21], v[22:23]
	v_and_b32_e32 v23, 0xffff0000, v25
	v_lshlrev_b32_e32 v24, 16, v25
	v_and_b32_e32 v25, 0xffff0000, v29
	v_lshlrev_b32_e32 v22, 16, v29
	v_pk_mul_f32 v[24:25], v[50:51], v[24:25] op_sel:[1,0] op_sel_hi:[0,1]
	s_waitcnt vmcnt(0)
	v_lshlrev_b32_e32 v52, 16, v32
	v_and_b32_e32 v53, 0xffff0000, v32
	v_lshlrev_b32_e32 v28, 16, v33
	v_and_b32_e32 v29, 0xffff0000, v33
	v_pk_fma_f32 v[22:23], v[50:51], v[22:23], v[24:25]
	v_pk_fma_f32 v[20:21], v[18:19], v[52:53], v[20:21] op_sel_hi:[0,1,1]
	v_pk_fma_f32 v[22:23], v[18:19], v[28:29], v[22:23] op_sel_hi:[0,1,1]
	v_lshlrev_b32_e32 v24, 16, v26
	v_and_b32_e32 v25, 0xffff0000, v30
	v_cvt_pk_bf16_f32 v20, v20, v21
	v_cvt_pk_bf16_f32 v21, v22, v23
	v_lshlrev_b32_e32 v22, 16, v30
	v_and_b32_e32 v23, 0xffff0000, v26
	v_pk_mul_f32 v[24:25], v[50:51], v[24:25] op_sel:[1,0] op_sel_hi:[0,1]
	v_pk_fma_f32 v[22:23], v[50:51], v[22:23], v[24:25]
	v_and_b32_e32 v25, 0xffff0000, v27
	v_lshlrev_b32_e32 v26, 16, v27
	v_and_b32_e32 v27, 0xffff0000, v31
	v_lshlrev_b32_e32 v28, 16, v34
	v_and_b32_e32 v29, 0xffff0000, v34
	v_lshlrev_b32_e32 v24, 16, v31
	v_pk_mul_f32 v[26:27], v[50:51], v[26:27] op_sel:[1,0] op_sel_hi:[0,1]
	v_pk_fma_f32 v[22:23], v[18:19], v[28:29], v[22:23] op_sel_hi:[0,1,1]
	v_lshlrev_b32_e32 v28, 16, v35
	v_and_b32_e32 v29, 0xffff0000, v35
	v_pk_fma_f32 v[24:25], v[50:51], v[24:25], v[26:27]
	v_lshlrev_b32_e32 v26, 16, v4
	v_pk_fma_f32 v[24:25], v[18:19], v[28:29], v[24:25] op_sel_hi:[0,1,1]
	v_and_b32_e32 v27, 0xffff0000, v8
	v_cvt_pk_bf16_f32 v22, v22, v23
	v_cvt_pk_bf16_f32 v23, v24, v25
	v_lshlrev_b32_e32 v24, 16, v8
	v_and_b32_e32 v25, 0xffff0000, v4
	v_pk_mul_f32 v[26:27], v[50:51], v[26:27] op_sel:[1,0] op_sel_hi:[0,1]
	v_lshlrev_b32_e32 v28, 16, v12
	v_and_b32_e32 v29, 0xffff0000, v12
	v_pk_fma_f32 v[24:25], v[50:51], v[24:25], v[26:27]
	v_lshlrev_b32_e32 v8, 16, v5
	v_pk_fma_f32 v[24:25], v[18:19], v[28:29], v[24:25] op_sel_hi:[0,1,1]
	v_cvt_pk_bf16_f32 v4, v24, v25
	v_lshlrev_b32_e32 v24, 16, v9
	v_and_b32_e32 v9, 0xffff0000, v9
	v_and_b32_e32 v25, 0xffff0000, v5
	v_pk_mul_f32 v[8:9], v[50:51], v[8:9] op_sel:[1,0] op_sel_hi:[0,1]
	v_lshlrev_b32_e32 v12, 16, v13
	v_and_b32_e32 v13, 0xffff0000, v13
	v_pk_fma_f32 v[8:9], v[50:51], v[24:25], v[8:9]
	v_lshlrev_b32_e32 v24, 16, v14
	v_pk_fma_f32 v[8:9], v[18:19], v[12:13], v[8:9] op_sel_hi:[0,1,1]
	v_lshlrev_b32_e32 v12, 16, v6
	v_and_b32_e32 v13, 0xffff0000, v10
	v_cvt_pk_bf16_f32 v5, v8, v9
	v_lshlrev_b32_e32 v8, 16, v10
	v_and_b32_e32 v9, 0xffff0000, v6
	v_pk_mul_f32 v[12:13], v[50:51], v[12:13] op_sel:[1,0] op_sel_hi:[0,1]
	v_and_b32_e32 v25, 0xffff0000, v14
	v_pk_fma_f32 v[8:9], v[50:51], v[8:9], v[12:13]
	v_lshlrev_b32_e32 v10, 16, v7
	v_pk_fma_f32 v[8:9], v[18:19], v[24:25], v[8:9] op_sel_hi:[0,1,1]
	v_cvt_pk_bf16_f32 v6, v8, v9
	v_lshlrev_b32_e32 v8, 16, v11
	v_and_b32_e32 v11, 0xffff0000, v11
	v_and_b32_e32 v9, 0xffff0000, v7
	v_pk_mul_f32 v[10:11], v[50:51], v[10:11] op_sel:[1,0] op_sel_hi:[0,1]
	v_pk_fma_f32 v[8:9], v[50:51], v[8:9], v[10:11]
	v_lshlrev_b32_e32 v10, 16, v15
	v_and_b32_e32 v11, 0xffff0000, v15
	v_pk_fma_f32 v[8:9], v[18:19], v[10:11], v[8:9] op_sel_hi:[0,1,1]
	v_cvt_pk_bf16_f32 v7, v8, v9
	v_lshl_add_u64 v[8:9], v[16:17], 0, v[46:47]
	v_lshl_add_u64 v[8:9], v[8:9], 0, v[48:49]
	global_store_dwordx4 v[8:9], v[20:23], off offset:2048
	global_store_dwordx4 v[8:9], v[4:7], off offset:2064
	s_andn2_b64 exec, exec, s[2:3]
	s_cbranch_execnz .LBB0_100
